# dense vector phase: fewer VALU (no per-tile -m copies; three wave-uniform boolean tests as one SALU op each instead of v_cndmask+v_cmp), on top of nt4
# speedup vs baseline: 1.0105x; 1.0105x over previous
; #define RESC(a) do { if (__any((a) < 1.f)) { if (hi == 0) al_l[r32] = (a); asm volatile("s_waitcnt lgkmcnt(0)" ::: "memory"); \
;     for (int d = 0; d < 4; ++d) for (int r = 0; r < 16; ++r) o[d][r] *= al_l[crow(r, hi)]; } } while (0)
; __device__ __forceinline__ void partialSM_neg(f32x16& p0, f32x16& p1, float& m_reg, f32x16& negm, float& alpha, int bounded) {
;   if (bounded) {
;     alpha = 1.f;
; #pragma unroll
;     for (int r = 0; r < 16; ++r) p0[r] = __builtin_amdgcn_exp2f(p0[r]);
;     return;
;   }
;   float pmax = p0[0];
; #pragma unroll
;   for (int r = 1; r < 16; ++r) pmax = fmaxf(pmax, p0[r]);
; #pragma unroll
;   for (int r = 0; r < 16; ++r) pmax = fmaxf(pmax, p1[r]);
;   { auto rr = __builtin_amdgcn_permlane32_swap(__float_as_uint(pmax), __float_as_uint(pmax), false, false);
;     pmax = fmaxf(__uint_as_float(rr[0]), __uint_as_float(rr[1])); }
;   if (__builtin_expect(__all(pmax <= THR), 1)) { alpha = 1.f; }
;     ...
;     for (int t = 0; t < NT; ++t) {
;       if (grpB && t + 3 < NT) DMA(t + 3, (t + 3) & 3);
;     ...
;       partialSM_neg(pA0, pA1, m_reg, negm, alA, i0); if (!i0) RESC(alA);
.LBB0_56:
	s_andn2_b64 s[44:45], exec, s[82:83]
	v_lshl_add_u64 v[66:67], v[208:209], 0, s[86:87]
	s_mov_b64 s[40:41], 0xf00c000
	v_lshl_add_u64 v[184:185], v[66:67], 0, s[40:41]
	s_mov_b64 s[40:41], 0xf00c080
	s_andn2_b64 vcc, exec, s[82:83]
	v_lshl_add_u64 v[182:183], v[210:211], 0, s[86:87]
	v_lshl_add_u64 v[178:179], v[212:213], 0, s[86:87]
	v_lshl_add_u64 v[180:181], v[66:67], 0, s[40:41]
	s_cbranch_vccnz .LBB0_58
	s_add_i32 s15, s86, 0xc000
	s_and_b32 s15, s15, 0xc000
	s_add_i32 s40, s13, s15
	s_mov_b32 m0, s40
	s_add_i32 s15, s14, s15
	global_load_lds_dwordx4 v[182:183], off
	s_mov_b32 m0, s15
	s_nop 0
	global_load_lds_dwordx4 v[184:185], off
	s_add_i32 m0, s40, 0x400
	s_nop 0
	global_load_lds_dwordx4 v[178:179], off
	s_add_i32 m0, s15, 0x400
	s_nop 0
	global_load_lds_dwordx4 v[180:181], off
.LBB0_58:
	s_andn2_b64 s[40:41], exec, s[80:81]
	s_andn2_b64 vcc, exec, s[80:81]
	v_mov_b32_e32 v242, 1.0
	s_cbranch_vccnz .LBB0_60
	v_max_f32_e32 v66, v99, v99
	v_max_f32_e32 v67, v98, v98
	v_max_f32_e32 v66, v67, v66
	v_max3_f32 v66, v66, v100, v101
	v_max3_f32 v66, v66, v102, v103
	v_max3_f32 v66, v66, v104, v105
	v_max3_f32 v66, v66, v106, v107
	v_max3_f32 v66, v66, v108, v109
	v_max3_f32 v66, v66, v110, v111
	v_max3_f32 v66, v66, v112, v113
	v_max3_f32 v66, v66, v82, v83
	v_max3_f32 v66, v66, v84, v85
	v_max3_f32 v66, v66, v86, v87
	v_max3_f32 v66, v66, v88, v89
	v_max3_f32 v66, v66, v90, v91
	v_max3_f32 v66, v66, v92, v93
	v_max3_f32 v66, v66, v94, v95
	v_max3_f32 v66, v66, v96, v97
	v_mov_b32_e32 v67, v66
	s_nop 1
	v_permlane32_swap_b32_e32 v66, v67
	v_max_f32_e32 v67, v67, v67
	v_max_f32_e32 v66, v66, v66
	v_max_f32_e32 v66, v66, v67
	v_cmp_ge_f32_e32 vcc, s91, v66
	s_cmp_eq_u64 vcc, exec
	v_mov_b32_e32 v242, 1.0
	s_cbranch_scc0 .LBB0_75

; #define PK4(P, BASE, OUT) do { unsigned a0 = cvtpk(P[BASE + 0], P[BASE + 1]), a1 = cvtpk(P[BASE + 2], P[BASE + 3]);   \
;     unsigned b0 = cvtpk(P[BASE + 4], P[BASE + 5]), b1 = cvtpk(P[BASE + 6], P[BASE + 7]);                              \
;     u32x4 w = {a0, a1, b0, b1}; OUT = *reinterpret_cast<bf16x8*>(&w); } while (0)
; #define PP_BAR(VM) do { if (VM) { asm volatile("s_waitcnt vmcnt(4) lgkmcnt(0)\n\ts_barrier" ::: "memory"); } else { asm volatile("s_waitcnt vmcnt(0) lgkmcnt(0)\n\ts_barrier" ::: "memory"); } } while (0)
; #define PP_BAR_PLAIN() asm volatile("s_waitcnt lgkmcnt(0)\n\ts_barrier" ::: "memory")
; __device__ __forceinline__ void finishSM(f32x16& p0, f32x16& p1, float alpha, float& l_reg, bf16x8& pa0, bf16x8& pa1, bf16x8& pa2, bf16x8& pa3) {
;   for (int r = 0; r < 16; ++r) p1[r] = __builtin_amdgcn_exp2f(p1[r]);
;   float ps = 0; for (int r = 0; r < 16; ++r) ps += p0[r]; for (int r = 0; r < 16; ++r) ps += p1[r];
;   { auto rr = __builtin_amdgcn_permlane32_swap(__float_as_uint(ps), __float_as_uint(ps), false, false);
;     ps = __uint_as_float(rr[0]) + __uint_as_float(rr[1]); }
;   l_reg = l_reg * alpha + ps;
;     ...
;   PK4(p0, 0, pa0); PK4(p0, 8, pa1); PK4(p1, 0, pa2); PK4(p1, 8, pa3);
;     ...
;       if (!(MK_PREB && t + 1 < NT)) { if (!grpB) PP_BAR(t + 2 < NT); else PP_BAR_PLAIN(); }
;       else if (!grpB) PP_BAR(t + 2 < NT);
;       if (!grpB && t + 3 < NT) DMA(t + 3, (t + 3) & 3);
.LBB0_65:
	v_exp_f32_e32 v98, v98
	v_exp_f32_e32 v99, v99
	v_exp_f32_e32 v100, v100
	v_exp_f32_e32 v101, v101
	v_exp_f32_e32 v102, v102
	v_add_f32_e32 v162, 0, v98
	v_exp_f32_e32 v103, v103
	v_add_f32_e32 v162, v99, v162
	v_exp_f32_e32 v104, v104
	v_add_f32_e32 v162, v100, v162
	v_exp_f32_e32 v105, v105
	v_add_f32_e32 v162, v101, v162
	v_exp_f32_e32 v106, v106
	v_add_f32_e32 v162, v102, v162
	v_exp_f32_e32 v107, v107
	v_add_f32_e32 v162, v103, v162
	v_exp_f32_e32 v108, v108
	v_add_f32_e32 v162, v104, v162
	v_exp_f32_e32 v109, v109
	v_add_f32_e32 v162, v105, v162
	v_exp_f32_e32 v110, v110
	v_add_f32_e32 v162, v106, v162
	v_exp_f32_e32 v111, v111
	v_add_f32_e32 v162, v107, v162
	v_exp_f32_e32 v112, v112
	v_add_f32_e32 v162, v108, v162
	v_exp_f32_e32 v113, v113
	v_add_f32_e32 v162, v109, v162
	v_exp_f32_e32 v82, v82
	v_add_f32_e32 v162, v110, v162
	v_exp_f32_e32 v83, v83
	v_add_f32_e32 v162, v111, v162
	v_exp_f32_e32 v84, v84
	v_add_f32_e32 v162, v112, v162
	v_exp_f32_e32 v85, v85
	v_add_f32_e32 v162, v113, v162
	v_exp_f32_e32 v86, v86
	v_add_f32_e32 v162, v82, v162
	v_exp_f32_e32 v87, v87
	v_add_f32_e32 v162, v83, v162
	v_exp_f32_e32 v88, v88
	v_add_f32_e32 v162, v84, v162
	v_exp_f32_e32 v89, v89
	v_add_f32_e32 v162, v85, v162
	v_exp_f32_e32 v90, v90
	v_add_f32_e32 v162, v86, v162
	v_exp_f32_e32 v91, v91
	v_add_f32_e32 v162, v87, v162
	v_exp_f32_e32 v92, v92
	v_add_f32_e32 v162, v88, v162
	v_exp_f32_e32 v93, v93
	v_add_f32_e32 v162, v89, v162
	v_exp_f32_e32 v94, v94
	v_add_f32_e32 v162, v90, v162
	v_exp_f32_e32 v95, v95
	v_add_f32_e32 v162, v91, v162
	v_exp_f32_e32 v96, v96
	v_add_f32_e32 v162, v92, v162
	v_exp_f32_e32 v97, v97
	v_add_f32_e32 v162, v93, v162
	v_add_f32_e32 v162, v94, v162
	v_add_f32_e32 v162, v95, v162
	v_add_f32_e32 v162, v96, v162
	v_add_f32_e32 v243, v97, v162
	v_mov_b32_e32 v245, v243
	v_cvt_pk_bf16_f32 v166, v82, v83
	s_nop 0
	v_permlane32_swap_b32_e32 v243, v245
	s_andn2_b64 s[42:43], exec, s[0:1]
	s_andn2_b64 vcc, exec, s[0:1]
	v_cvt_pk_bf16_f32 v174, v98, v99
	v_cvt_pk_bf16_f32 v175, v100, v101
	v_cvt_pk_bf16_f32 v176, v102, v103
	v_cvt_pk_bf16_f32 v177, v104, v105
	v_cvt_pk_bf16_f32 v170, v106, v107
	v_cvt_pk_bf16_f32 v171, v108, v109
	v_cvt_pk_bf16_f32 v172, v110, v111
	v_cvt_pk_bf16_f32 v173, v112, v113
	v_cvt_pk_bf16_f32 v167, v84, v85
	v_cvt_pk_bf16_f32 v168, v86, v87
	v_cvt_pk_bf16_f32 v169, v88, v89
	v_cvt_pk_bf16_f32 v162, v90, v91
	v_cvt_pk_bf16_f32 v163, v92, v93
	v_cvt_pk_bf16_f32 v164, v94, v95
	v_cvt_pk_bf16_f32 v165, v96, v97
	s_cbranch_vccnz .LBB0_67
	s_add_i32 s15, s86, 0xc000
	s_and_b32 s15, s15, 0xc000
	s_add_i32 s84, s13, s15
	s_waitcnt vmcnt(4) lgkmcnt(0)
	s_barrier
	s_mov_b32 m0, s84
	s_add_i32 s15, s14, s15
	global_load_lds_dwordx4 v[182:183], off
	s_mov_b32 m0, s15
	s_nop 0
	global_load_lds_dwordx4 v[184:185], off
	s_add_i32 m0, s84, 0x400
	s_nop 0
	global_load_lds_dwordx4 v[178:179], off
	s_add_i32 m0, s15, 0x400
	s_nop 0
	global_load_lds_dwordx4 v[180:181], off
